# plus: prologue weight-conversion items rebalanced away from the 32 workgroups that own two adaLN items
# speedup vs baseline: 1.0120x; 1.0005x over previous
; #define LAS __attribute__((address_space(3)))
; __device__ __forceinline__ unsigned pk2(float lo, float hi) { return f2bf(lo) | (f2bf(hi) << 16); }
; __device__ __forceinline__ void cvt_item(const float* W, int K, int Ns, int src0, const float* gain, float cscale, bf16* WT, int n0, int k0, LAS float* scr, int lane) {
;     ...
;     const int c = lane & 7;
; #pragma unroll
;     for (int j = 0; j < 4; ++j) {
;         const int n = (lane >> 3) + 8 * j; const LAS float* s = scr + (8 * c) * 33 + n;
;         v4u o; o.x = pk2(s[0 * 33], s[1 * 33]); o.y = pk2(s[2 * 33], s[3 * 33]); o.z = pk2(s[4 * 33], s[5 * 33]); o.w = pk2(s[6 * 33], s[7 * 33]);
;         *(v4u*)(WT + (size_t)(n0 + n) * K + k0 + 8 * c) = o;
;     }
;     asm volatile("s_waitcnt lgkmcnt(0)" ::: "memory");
; __device__ __forceinline__ void p0_prologue(Frame& F, const Args& A, unsigned char* ws) {
;     ...
;     for (int it = gw; it < DEPTH * ITEMS_PER_LAYER; it += NGW) {
;         const int l = it / ITEMS_PER_LAYER; int r = it % ITEMS_PER_LAYER; int mat = 0;
;         for (;;) { const int n = mat_items(mat); if (r < n) break; r -= n; ++mat; }
.LBB0_656:
	ds_write_b32 v13, v4 offset:8184
	s_waitcnt lgkmcnt(0)
	ds_read_b32 v3, v9
	ds_read_b32 v4, v9 offset:132
	ds_read_b32 v5, v9 offset:264
	ds_read_b32 v6, v9 offset:396
	ds_read_b32 v7, v9 offset:528
	ds_read_b32 v16, v9 offset:660
	ds_read_b32 v17, v9 offset:792
	ds_read_b32 v18, v9 offset:924
	s_waitcnt lgkmcnt(7)
	v_bfe_u32 v19, v3, 16, 1
	v_add3_u32 v3, v3, v19, s66
	s_waitcnt lgkmcnt(6)
	v_bfe_u32 v19, v4, 16, 1
	v_lshrrev_b32_e32 v3, 16, v3
	v_add3_u32 v4, v4, v19, s66
	v_and_or_b32 v4, v4, s94, v3
	s_waitcnt lgkmcnt(5)
	v_bfe_u32 v3, v5, 16, 1
	v_add3_u32 v3, v5, v3, s66
	s_waitcnt lgkmcnt(4)
	v_bfe_u32 v5, v6, 16, 1
	s_mul_i32 s7, s17, 0x2d10000
	v_lshrrev_b32_e32 v3, 16, v3
	v_add3_u32 v5, v6, v5, s66
	s_mul_hi_i32 s6, s17, 0x2d10000
	s_add_u32 s12, s5, s7
	v_and_or_b32 v5, v5, s94, v3
	s_waitcnt lgkmcnt(3)
	v_bfe_u32 v3, v7, 16, 1
	s_addc_u32 s13, s16, s6
	s_lshl_b64 s[6:7], s[10:11], 1
	v_add3_u32 v3, v7, v3, s66
	s_waitcnt lgkmcnt(2)
	v_bfe_u32 v6, v16, 16, 1
	s_add_u32 s10, s12, s6
	v_lshrrev_b32_e32 v3, 16, v3
	v_add3_u32 v6, v16, v6, s66
	s_addc_u32 s11, s13, s7
	s_lshl_b64 s[6:7], s[14:15], 1
	v_and_or_b32 v6, v6, s94, v3
	s_waitcnt lgkmcnt(1)
	v_bfe_u32 v3, v17, 16, 1
	s_add_u32 s6, s10, s6
	v_add3_u32 v3, v17, v3, s66
	s_waitcnt lgkmcnt(0)
	v_bfe_u32 v7, v18, 16, 1
	s_addc_u32 s7, s11, s7
	v_lshrrev_b32_e32 v3, 16, v3
	v_add3_u32 v7, v18, v7, s66
	v_lshl_add_u64 v[14:15], s[6:7], 0, v[192:193]
	v_and_or_b32 v7, v7, s94, v3
	v_or_b32_e32 v3, s20, v8
	s_ashr_i32 s6, s20, 31
	v_mul_lo_u32 v18, s9, v3
	s_mul_i32 s10, s8, s6
	v_mad_u64_u32 v[16:17], s[6:7], s8, v3, 0
	v_add3_u32 v17, v17, s10, v18
	v_lshl_add_u64 v[16:17], v[16:17], 1, v[14:15]
	flat_store_dwordx4 v[16:17], v[4:7]
	ds_read_b32 v3, v9 offset:32
	ds_read_b32 v4, v9 offset:164
	ds_read_b32 v5, v9 offset:296
	ds_read_b32 v6, v9 offset:428
	ds_read_b32 v7, v9 offset:560
	ds_read_b32 v16, v9 offset:692
	ds_read_b32 v17, v9 offset:824
	ds_read_b32 v18, v9 offset:956
	s_waitcnt lgkmcnt(0)
	v_bfe_u32 v19, v3, 16, 1
	v_add3_u32 v3, v3, v19, s66
	v_bfe_u32 v19, v4, 16, 1
	v_lshrrev_b32_e32 v3, 16, v3
	v_add3_u32 v4, v4, v19, s66
	v_and_or_b32 v4, v4, s94, v3
	v_bfe_u32 v3, v5, 16, 1
	v_add3_u32 v3, v5, v3, s66
	v_bfe_u32 v5, v6, 16, 1
	v_lshrrev_b32_e32 v3, 16, v3
	v_add3_u32 v5, v6, v5, s66
	v_and_or_b32 v5, v5, s94, v3
	v_bfe_u32 v3, v7, 16, 1
	v_add3_u32 v3, v7, v3, s66
	v_bfe_u32 v6, v16, 16, 1
	v_lshrrev_b32_e32 v3, 16, v3
	v_add3_u32 v6, v16, v6, s66
	v_and_or_b32 v6, v6, s94, v3
	v_bfe_u32 v3, v17, 16, 1
	v_add3_u32 v3, v17, v3, s66
	v_bfe_u32 v7, v18, 16, 1
	v_lshrrev_b32_e32 v3, 16, v3
	v_add3_u32 v7, v18, v7, s66
	v_and_or_b32 v7, v7, s94, v3
	v_or_b32_e32 v3, s20, v10
	v_mul_lo_u32 v18, s9, v3
	v_mad_u64_u32 v[16:17], s[6:7], s8, v3, 0
	v_add3_u32 v17, v17, s10, v18
	v_lshl_add_u64 v[16:17], v[16:17], 1, v[14:15]
	flat_store_dwordx4 v[16:17], v[4:7]
	ds_read_b32 v3, v9 offset:64
	ds_read_b32 v4, v9 offset:196
	ds_read_b32 v5, v9 offset:328
	ds_read_b32 v6, v9 offset:460
	ds_read_b32 v7, v9 offset:592
	ds_read_b32 v16, v9 offset:724
	ds_read_b32 v17, v9 offset:856
	ds_read_b32 v18, v9 offset:988
	s_waitcnt lgkmcnt(0)
	v_bfe_u32 v19, v3, 16, 1
	v_add3_u32 v3, v3, v19, s66
	v_bfe_u32 v19, v4, 16, 1
	v_lshrrev_b32_e32 v3, 16, v3
	v_add3_u32 v4, v4, v19, s66
	v_and_or_b32 v4, v4, s94, v3
	v_bfe_u32 v3, v5, 16, 1
	v_add3_u32 v3, v5, v3, s66
	v_bfe_u32 v5, v6, 16, 1
	v_lshrrev_b32_e32 v3, 16, v3
	v_add3_u32 v5, v6, v5, s66
	v_and_or_b32 v5, v5, s94, v3
	v_bfe_u32 v3, v7, 16, 1
	v_add3_u32 v3, v7, v3, s66
	v_bfe_u32 v6, v16, 16, 1
	v_lshrrev_b32_e32 v3, 16, v3
	v_add3_u32 v6, v16, v6, s66
	v_and_or_b32 v6, v6, s94, v3
	v_bfe_u32 v3, v17, 16, 1
	v_add3_u32 v3, v17, v3, s66
	v_bfe_u32 v7, v18, 16, 1
	v_lshrrev_b32_e32 v3, 16, v3
	v_add3_u32 v7, v18, v7, s66
	v_and_or_b32 v7, v7, s94, v3
	v_or_b32_e32 v3, s20, v11
	v_mul_lo_u32 v18, s9, v3
	v_mad_u64_u32 v[16:17], s[6:7], s8, v3, 0
	v_add3_u32 v17, v17, s10, v18
	v_lshl_add_u64 v[16:17], v[16:17], 1, v[14:15]
	flat_store_dwordx4 v[16:17], v[4:7]
	ds_read_b32 v3, v9 offset:96
	ds_read_b32 v4, v9 offset:228
	ds_read_b32 v5, v9 offset:360
	ds_read_b32 v6, v9 offset:492
	ds_read_b32 v7, v9 offset:624
	ds_read_b32 v16, v9 offset:756
	ds_read_b32 v17, v9 offset:888
	ds_read_b32 v18, v9 offset:1020
	s_waitcnt lgkmcnt(0)
	v_bfe_u32 v19, v3, 16, 1
	v_add3_u32 v3, v3, v19, s66
	v_bfe_u32 v19, v4, 16, 1
	v_lshrrev_b32_e32 v3, 16, v3
	v_add3_u32 v4, v4, v19, s66
	v_and_or_b32 v4, v4, s94, v3
	v_bfe_u32 v3, v5, 16, 1
	v_add3_u32 v3, v5, v3, s66
	v_bfe_u32 v5, v6, 16, 1
	v_lshrrev_b32_e32 v3, 16, v3
	v_add3_u32 v5, v6, v5, s66
	v_and_or_b32 v5, v5, s94, v3
	v_bfe_u32 v3, v7, 16, 1
	v_add3_u32 v3, v7, v3, s66
	v_bfe_u32 v6, v16, 16, 1
	v_lshrrev_b32_e32 v3, 16, v3
	v_add3_u32 v6, v16, v6, s66
	v_and_or_b32 v6, v6, s94, v3
	v_bfe_u32 v3, v17, 16, 1
	v_add3_u32 v3, v17, v3, s66
	v_bfe_u32 v7, v18, 16, 1
	v_lshrrev_b32_e32 v3, 16, v3
	v_add3_u32 v7, v18, v7, s66
	v_and_or_b32 v7, v7, s94, v3
	v_or_b32_e32 v3, s20, v12
	v_mul_lo_u32 v18, s9, v3
	v_mad_u64_u32 v[16:17], s[6:7], s8, v3, 0
	v_add3_u32 v17, v17, s10, v18
	v_lshl_add_u64 v[14:15], v[16:17], 1, v[14:15]
	flat_store_dwordx4 v[14:15], v[4:7]
	s_waitcnt lgkmcnt(0)
	s_cmp_lg_u32 s4, 0x800
	s_cbranch_scc1 .Lcv_generic
	s_cmp_ge_u32 s2, 0x4000
	s_cbranch_scc1 .Lcv_phase2
	s_add_i32 s2, s2, 0x800
	s_cmp_lt_u32 s2, 0x4000
	s_cbranch_scc1 .Lcv_check
	s_cmp_lt_u32 s33, 32
	s_cbranch_scc1 .LBB0_921
	s_lshl_b32 s2, s33, 3
	s_add_i32 s2, s2, s83
	s_add_i32 s2, s2, 0x3f00
	s_branch .Lcv_check
.Lcv_phase2:
	s_add_i32 s2, s2, 0x700
	s_branch .Lcv_check

; __device__ __forceinline__ void p0_prologue(Frame& F, const Args& A, unsigned char* ws) {
;     ...
;     for (int it = gw; it < DEPTH * ITEMS_PER_LAYER; it += NGW) {
.Lcv_check:
	s_cmpk_gt_i32 s2, 0x5a1f
	s_cbranch_scc1 .LBB0_921
